# adds: sample-row dt projection loads (32 ushort) issued back to back instead of one pair per wait
# baseline (speedup 1.0000x reference)
.LBB0_583:
	s_andn2_b64 vcc, exec, s[4:5]
	s_cbranch_vccnz .LBB0_589
	s_lshl_b64 s[4:5], s[12:13], 11
	v_readlane_b32 s14, v253, 44
	v_and_b32_e32 v3, 63, v2
	v_readlane_b32 s15, v253, 45
	s_add_u32 s4, s14, s4
	s_addc_u32 s5, s15, s5
	v_lshlrev_b32_e32 v0, 1, v3
	v_ashrrev_i32_e32 v4, 6, v2
	v_lshlrev_b32_e32 v6, 10, v4
	v_ashrrev_i32_e32 v7, 31, v6
	v_lshl_add_u64 v[6:7], v[6:7], 1, s[16:17]
	v_lshl_add_u64 v[6:7], v[6:7], 0, v[0:1]
	global_load_ushort v36, v0, s[4:5]
	global_load_ushort v37, v0, s[4:5] offset:128
	global_load_ushort v38, v0, s[4:5] offset:256
	global_load_ushort v39, v0, s[4:5] offset:384
	global_load_ushort v40, v0, s[4:5] offset:512
	global_load_ushort v41, v0, s[4:5] offset:640
	global_load_ushort v42, v0, s[4:5] offset:768
	global_load_ushort v43, v0, s[4:5] offset:896
	global_load_ushort v44, v0, s[4:5] offset:1024
	global_load_ushort v45, v0, s[4:5] offset:1152
	global_load_ushort v46, v0, s[4:5] offset:1280
	global_load_ushort v47, v0, s[4:5] offset:1408
	global_load_ushort v48, v0, s[4:5] offset:1536
	global_load_ushort v49, v0, s[4:5] offset:1664
	global_load_ushort v50, v0, s[4:5] offset:1792
	global_load_ushort v51, v0, s[4:5] offset:1920
	global_load_ushort v52, v[6:7], off
	global_load_ushort v53, v[6:7], off offset:128
	global_load_ushort v54, v[6:7], off offset:256
	global_load_ushort v55, v[6:7], off offset:384
	global_load_ushort v56, v[6:7], off offset:512
	global_load_ushort v57, v[6:7], off offset:640
	global_load_ushort v58, v[6:7], off offset:768
	global_load_ushort v59, v[6:7], off offset:896
	global_load_ushort v60, v[6:7], off offset:1024
	global_load_ushort v61, v[6:7], off offset:1152
	global_load_ushort v62, v[6:7], off offset:1280
	global_load_ushort v63, v[6:7], off offset:1408
	global_load_ushort v64, v[6:7], off offset:1536
	global_load_ushort v65, v[6:7], off offset:1664
	global_load_ushort v66, v[6:7], off offset:1792
	global_load_ushort v67, v[6:7], off offset:1920
	s_waitcnt vmcnt(0)
	v_lshlrev_b32_e32 v36, 16, v36
	v_lshlrev_b32_e32 v37, 16, v37
	v_lshlrev_b32_e32 v38, 16, v38
	v_lshlrev_b32_e32 v39, 16, v39
	v_lshlrev_b32_e32 v40, 16, v40
	v_lshlrev_b32_e32 v41, 16, v41
	v_lshlrev_b32_e32 v42, 16, v42
	v_lshlrev_b32_e32 v43, 16, v43
	v_lshlrev_b32_e32 v44, 16, v44
	v_lshlrev_b32_e32 v45, 16, v45
	v_lshlrev_b32_e32 v46, 16, v46
	v_lshlrev_b32_e32 v47, 16, v47
	v_lshlrev_b32_e32 v48, 16, v48
	v_lshlrev_b32_e32 v49, 16, v49
	v_lshlrev_b32_e32 v50, 16, v50
	v_lshlrev_b32_e32 v51, 16, v51
	v_lshlrev_b32_e32 v52, 16, v52
	v_lshlrev_b32_e32 v53, 16, v53
	v_lshlrev_b32_e32 v54, 16, v54
	v_lshlrev_b32_e32 v55, 16, v55
	v_lshlrev_b32_e32 v56, 16, v56
	v_lshlrev_b32_e32 v57, 16, v57
	v_lshlrev_b32_e32 v58, 16, v58
	v_lshlrev_b32_e32 v59, 16, v59
	v_lshlrev_b32_e32 v60, 16, v60
	v_lshlrev_b32_e32 v61, 16, v61
	v_lshlrev_b32_e32 v62, 16, v62
	v_lshlrev_b32_e32 v63, 16, v63
	v_lshlrev_b32_e32 v64, 16, v64
	v_lshlrev_b32_e32 v65, 16, v65
	v_lshlrev_b32_e32 v66, 16, v66
	v_lshlrev_b32_e32 v67, 16, v67
	v_fma_f32 v8, v36, v52, 0
	v_mul_f32_e32 v5, v37, v37
	v_fmac_f32_e32 v5, v36, v36
	v_fmac_f32_e32 v8, v37, v53
	v_fmac_f32_e32 v5, v38, v38
	v_fmac_f32_e32 v8, v38, v54
	v_fmac_f32_e32 v5, v39, v39
	v_fmac_f32_e32 v8, v39, v55
	v_fmac_f32_e32 v5, v40, v40
	v_fmac_f32_e32 v8, v40, v56
	v_fmac_f32_e32 v5, v41, v41
	v_fmac_f32_e32 v8, v41, v57
	v_fmac_f32_e32 v5, v42, v42
	v_fmac_f32_e32 v8, v42, v58
	v_fmac_f32_e32 v5, v43, v43
	v_fmac_f32_e32 v8, v43, v59
	v_fmac_f32_e32 v5, v44, v44
	v_fmac_f32_e32 v8, v44, v60
	v_fmac_f32_e32 v5, v45, v45
	v_fmac_f32_e32 v8, v45, v61
	v_fmac_f32_e32 v5, v46, v46
	v_fmac_f32_e32 v8, v46, v62
	v_fmac_f32_e32 v5, v47, v47
	v_fmac_f32_e32 v8, v47, v63
	v_fmac_f32_e32 v5, v48, v48
	v_fmac_f32_e32 v8, v48, v64
	v_fmac_f32_e32 v5, v49, v49
	v_fmac_f32_e32 v8, v49, v65
	v_fmac_f32_e32 v5, v50, v50
	v_fmac_f32_e32 v8, v50, v66
	v_fmac_f32_e32 v5, v51, v51
	v_fmac_f32_e32 v8, v51, v67
	v_and_b32_e32 v0, 64, v243
	v_add_u32_e32 v6, 64, v0
	v_xor_b32_e32 v0, 32, v243
	v_cmp_lt_i32_e32 vcc, v0, v6
	s_nop 1
	v_cndmask_b32_e32 v0, v243, v0, vcc
	v_lshlrev_b32_e32 v7, 2, v0
	ds_bpermute_b32 v0, v7, v8
	ds_bpermute_b32 v7, v7, v5
	s_waitcnt lgkmcnt(1)
	v_add_f32_e32 v0, v8, v0
	v_xor_b32_e32 v8, 16, v243
	v_cmp_lt_i32_e32 vcc, v8, v6
	s_waitcnt lgkmcnt(0)
	v_add_f32_e32 v5, v5, v7
	v_cndmask_b32_e32 v8, v243, v8, vcc
	v_lshlrev_b32_e32 v8, 2, v8
	ds_bpermute_b32 v9, v8, v0
	ds_bpermute_b32 v7, v8, v5
	s_waitcnt lgkmcnt(1)
	v_add_f32_e32 v0, v0, v9
	v_xor_b32_e32 v9, 8, v243
	v_cmp_lt_i32_e32 vcc, v9, v6
	s_waitcnt lgkmcnt(0)
	v_add_f32_e32 v5, v5, v7
	v_cndmask_b32_e32 v9, v243, v9, vcc
	v_lshlrev_b32_e32 v9, 2, v9
	ds_bpermute_b32 v10, v9, v0
	ds_bpermute_b32 v7, v9, v5
	s_waitcnt lgkmcnt(1)
	v_add_f32_e32 v0, v0, v10
	v_xor_b32_e32 v10, 4, v243
	v_cmp_lt_i32_e32 vcc, v10, v6
	s_waitcnt lgkmcnt(0)
	v_add_f32_e32 v5, v5, v7
	v_cndmask_b32_e32 v10, v243, v10, vcc
	v_lshlrev_b32_e32 v10, 2, v10
	ds_bpermute_b32 v11, v10, v0
	ds_bpermute_b32 v7, v10, v5
	s_waitcnt lgkmcnt(1)
	v_add_f32_e32 v0, v0, v11
	v_xor_b32_e32 v11, 2, v243
	v_cmp_lt_i32_e32 vcc, v11, v6
	s_waitcnt lgkmcnt(0)
	v_add_f32_e32 v5, v5, v7
	v_cndmask_b32_e32 v11, v243, v11, vcc
	v_lshlrev_b32_e32 v11, 2, v11
	ds_bpermute_b32 v12, v11, v0
	ds_bpermute_b32 v7, v11, v5
	s_waitcnt lgkmcnt(1)
	v_add_f32_e32 v0, v0, v12
	v_xor_b32_e32 v12, 1, v243
	v_cmp_lt_i32_e32 vcc, v12, v6
	s_waitcnt lgkmcnt(0)
	v_add_f32_e32 v5, v5, v7
	v_cndmask_b32_e32 v6, v243, v12, vcc
	v_lshlrev_b32_e32 v12, 2, v6
	ds_bpermute_b32 v6, v12, v0
	ds_bpermute_b32 v7, v12, v5
	v_cmp_eq_u32_e32 vcc, 0, v3
	s_and_saveexec_b64 s[4:5], vcc
	s_cbranch_execz .LBB0_588
	s_waitcnt lgkmcnt(0)
	v_add_f32_e32 v3, v5, v7
	v_add_f32_e32 v5, v0, v6
	v_fmamk_f32 v0, v3, 0x3a800000, v241
	s_mov_b32 s9, 0x800000
	v_readlane_b32 s14, v253, 42
	v_cmp_gt_f32_e32 vcc, s9, v0
	v_mul_f32_e32 v3, 0x4b800000, v0
	v_readlane_b32 s15, v253, 43
	v_cndmask_b32_e32 v0, v0, v3, vcc
	s_load_dwordx2 s[14:15], s[14:15], 0x88
	v_rsq_f32_e32 v0, v0
	v_readlane_b32 s9, v253, 58
	v_mul_f32_e32 v3, 0x45800000, v0
	s_nop 0
	v_add_u32_e32 v6, s9, v4
	v_ashrrev_i32_e32 v7, 31, v6
	s_waitcnt lgkmcnt(0)
	v_lshl_add_u64 v[6:7], v[6:7], 2, s[14:15]
	v_cndmask_b32_e32 v3, v0, v3, vcc
	global_load_dword v0, v[6:7], off
	s_mov_b32 s9, 0x41a00000
	s_waitcnt vmcnt(0)
	v_fmac_f32_e32 v0, v5, v3
	v_cmp_nlt_f32_e32 vcc, s9, v0
	s_and_saveexec_b64 s[14:15], vcc
	s_cbranch_execz .LBB0_587
	v_mul_f32_e32 v0, 0x3fb8aa3b, v0
	v_exp_f32_e32 v0, v0
	s_mov_b32 s9, 0x3f2aaaab
	v_add_f32_e32 v3, 1.0, v0
	v_frexp_mant_f32_e32 v8, v3
	v_cvt_f64_f32_e32 v[6:7], v3
	v_add_f32_e32 v5, -1.0, v3
	v_frexp_exp_i32_f64_e32 v6, v[6:7]
	v_cmp_gt_f32_e32 vcc, s9, v8
	v_sub_f32_e32 v9, v5, v3
	v_sub_f32_e32 v5, v0, v5
	v_subbrev_co_u32_e32 v14, vcc, 0, v6, vcc
	v_add_f32_e32 v9, 1.0, v9
	v_sub_u32_e32 v6, 0, v14
	v_add_f32_e32 v5, v5, v9
	v_ldexp_f32 v3, v3, v6
	v_ldexp_f32 v5, v5, v6
	v_add_f32_e32 v6, -1.0, v3
	v_add_f32_e32 v7, 1.0, v6
	v_sub_f32_e32 v7, v3, v7
	v_add_f32_e32 v8, v5, v7
	v_add_f32_e32 v7, 1.0, v3
	v_add_f32_e32 v9, -1.0, v7
	v_sub_f32_e32 v3, v3, v9
	v_add_f32_e32 v3, v5, v3
	v_add_f32_e32 v5, v7, v3
	v_rcp_f32_e32 v15, v5
	v_sub_f32_e32 v7, v5, v7
	v_sub_f32_e32 v3, v3, v7
	v_add_f32_e32 v7, v6, v8
	v_sub_f32_e32 v6, v7, v6
	v_mul_f32_e32 v17, v7, v15
	v_sub_f32_e32 v16, v8, v6
	v_mul_f32_e32 v8, v5, v17
	v_fma_f32 v10, v17, v5, -v8
	v_fmac_f32_e32 v10, v17, v3
	v_add_f32_e32 v6, v8, v10
	v_sub_f32_e32 v9, v7, v6
	v_pk_add_f32 v[12:13], v[6:7], v[8:9] neg_lo:[0,1] neg_hi:[0,1]
	v_mov_b32_e32 v11, v6
	v_pk_add_f32 v[6:7], v[12:13], v[10:11] neg_lo:[0,1] neg_hi:[0,1]
	s_mov_b32 s9, 0x3f317218
	v_add_f32_e32 v7, v16, v7
	v_add_f32_e32 v6, v6, v7
	v_add_f32_e32 v7, v9, v6
	v_mul_f32_e32 v16, v15, v7
	v_mul_f32_e32 v8, v5, v16
	v_fma_f32 v10, v16, v5, -v8
	v_fmac_f32_e32 v10, v16, v3
	v_sub_f32_e32 v3, v9, v7
	v_add_f32_e32 v3, v6, v3
	v_add_f32_e32 v6, v8, v10
	v_sub_f32_e32 v9, v7, v6
	v_pk_add_f32 v[12:13], v[6:7], v[8:9] neg_lo:[0,1] neg_hi:[0,1]
	v_mov_b32_e32 v11, v6
	v_pk_add_f32 v[6:7], v[12:13], v[10:11] neg_lo:[0,1] neg_hi:[0,1]
	v_add_f32_e32 v5, v17, v16
	v_add_f32_e32 v3, v3, v7
	v_add_f32_e32 v3, v6, v3
	v_add_f32_e32 v3, v9, v3
	v_sub_f32_e32 v6, v5, v17
	v_mul_f32_e32 v3, v15, v3
	v_sub_f32_e32 v6, v16, v6
	v_add_f32_e32 v3, v6, v3
	v_add_f32_e32 v7, v5, v3
	v_mul_f32_e32 v8, v7, v7
	v_mov_b32_e32 v6, 0x3ecc95a3
	v_fmamk_f32 v6, v8, 0x3e9b6dac, v6
	v_fmaak_f32 v195, v8, v6, 0x3f2aaada
	v_cvt_f32_i32_e32 v6, v14
	v_sub_f32_e32 v5, v7, v5
	v_ldexp_f32 v9, v7, 1
	v_mul_f32_e32 v7, v7, v8
	v_pk_mul_f32 v[10:11], v[6:7], v[194:195]
	v_sub_f32_e32 v3, v3, v5
	v_fma_f32 v8, v6, s9, -v10
	v_fmac_f32_e32 v8, 0xb102e308, v6
	v_pk_add_f32 v[6:7], v[10:11], v[8:9]
	v_ldexp_f32 v3, v3, 1
	v_sub_f32_e32 v5, v7, v9
	v_sub_f32_e32 v5, v11, v5
	v_add_f32_e32 v13, v3, v5
	v_mov_b32_e32 v12, v10
	v_pk_add_f32 v[10:11], v[6:7], v[10:11] neg_lo:[0,1] neg_hi:[0,1]
	v_pk_add_f32 v[14:15], v[6:7], v[12:13]
	v_mov_b32_e32 v9, v6
	v_mov_b32_e32 v11, v15
	v_pk_add_f32 v[16:17], v[8:9], v[10:11] neg_lo:[0,1] neg_hi:[0,1]
	v_pk_add_f32 v[8:9], v[8:9], v[10:11]
	v_mov_b32_e32 v12, v13
	v_pk_add_f32 v[10:11], v[8:9], v[6:7] op_sel:[1,0] op_sel_hi:[0,1] neg_lo:[0,1] neg_hi:[0,1]
	v_pk_add_f32 v[18:19], v[14:15], v[10:11] op_sel_hi:[1,0] neg_lo:[0,1] neg_hi:[0,1]
	v_mov_b32_e32 v14, v15
	v_mov_b32_e32 v15, v9
	v_pk_mov_b32 v[10:11], v[6:7], v[10:11] op_sel:[1,0]
	v_mov_b32_e32 v13, v6
	v_pk_add_f32 v[10:11], v[14:15], v[10:11] neg_lo:[0,1] neg_hi:[0,1]
	v_mov_b32_e32 v18, v16
	v_pk_add_f32 v[6:7], v[12:13], v[10:11] neg_lo:[0,1] neg_hi:[0,1]
	v_mov_b32_e32 v17, v9
	v_pk_add_f32 v[10:11], v[18:19], v[6:7]
	s_mov_b32 s9, 0x7f800000
	v_pk_add_f32 v[12:13], v[10:11], v[10:11] op_sel:[0,1] op_sel_hi:[1,0]
	v_cmp_neq_f32_e32 vcc, s9, v0
	v_pk_add_f32 v[8:9], v[8:9], v[12:13] op_sel:[1,0] op_sel_hi:[0,1]
	v_mov_b32_e32 v11, v8
	v_pk_add_f32 v[14:15], v[10:11], v[16:17] neg_lo:[0,1] neg_hi:[0,1]
	v_mov_b32_e32 v7, v12
	v_sub_f32_e32 v3, v10, v14
	v_pk_add_f32 v[6:7], v[6:7], v[14:15] neg_lo:[0,1] neg_hi:[0,1]
	v_sub_f32_e32 v3, v16, v3
	v_add_f32_e32 v3, v6, v3
	v_add_f32_e32 v3, v3, v7
	v_add_f32_e32 v3, v8, v3
	v_mov_b32_e32 v5, 0x7f800000
	v_cndmask_b32_e32 v3, v5, v3, vcc
	v_cmp_ngt_f32_e32 vcc, -1.0, v0
	s_mov_b32 s9, 0x33800000
	s_nop 0
	v_cndmask_b32_e32 v3, v248, v3, vcc
	v_cmp_neq_f32_e32 vcc, -1.0, v0
	s_nop 1
	v_cndmask_b32_e32 v3, v244, v3, vcc
	v_cmp_lt_f32_e64 vcc, |v0|, s9
	s_nop 1
	v_cndmask_b32_e32 v0, v3, v0, vcc

.LBB0_595:
	global_load_ushort v14, v[6:7], off
	v_add_u32_e32 v0, 0x200, v0
	v_lshl_add_u64 v[6:7], v[6:7], 0, s[34:35]
	s_waitcnt vmcnt(0)
	v_lshlrev_b32_e32 v18, 16, v14
	v_lshl_add_u64 v[14:15], v[12:13], 0, s[10:11]
	v_add_co_u32_e32 v16, vcc, 0x1000, v14
	global_load_dword v19, v[14:15], off
	s_nop 0
	v_addc_co_u32_e32 v17, vcc, 0, v15, vcc
	global_load_dword v20, v[16:17], off
	v_add_co_u32_e32 v14, vcc, 0x2000, v14
	s_nop 1
	v_addc_co_u32_e32 v15, vcc, 0, v15, vcc
	global_load_dword v21, v[14:15], off
	v_lshl_add_u64 v[14:15], v[4:5], 0, s[10:11]
	global_load_dword v22, v[14:15], off
	v_lshl_add_u64 v[14:15], v[10:11], 0, s[10:11]
	global_load_dword v16, v[14:15], off
	s_waitcnt vmcnt(0)
	v_fmac_f32_e32 v22, v19, v16
	v_add_co_u32_e32 v16, vcc, 0x1000, v14
	s_nop 1
	v_addc_co_u32_e32 v17, vcc, 0, v15, vcc
	global_load_dword v16, v[16:17], off
	s_waitcnt vmcnt(0)
	v_fmac_f32_e32 v22, v20, v16
	v_add_co_u32_e32 v16, vcc, s30, v14
	s_nop 1
	v_addc_co_u32_e32 v17, vcc, 0, v15, vcc
	v_add_co_u32_e32 v14, vcc, 0x3000, v14
	global_load_dword v16, v[16:17], off
	s_nop 0
	v_addc_co_u32_e32 v15, vcc, 0, v15, vcc
	global_load_dword v14, v[14:15], off
	s_waitcnt vmcnt(1)
	v_fmac_f32_e32 v22, v21, v16
	s_waitcnt vmcnt(0)
	v_fmac_f32_e32 v22, v14, v18
	v_mul_f32_e32 v14, 0xbfb8aa3b, v22
	v_exp_f32_e32 v14, v14
	s_nop 0
	v_add_f32_e32 v14, 1.0, v14
	v_rcp_f32_e32 v14, v14
	s_nop 0
	v_mul_f32_e32 v14, v22, v14
	v_cvt_pk_bf16_f32 v14, v14, v1
	global_store_short v[8:9], v14, off
	v_lshl_add_u64 v[14:15], v[2:3], 0, s[10:11]
	v_add_co_u32_e32 v16, vcc, 0x1a146000, v14
	s_add_u32 s10, s10, 0x800
	s_nop 0
	v_addc_co_u32_e32 v17, vcc, 0, v15, vcc
	global_store_dword v[16:17], v20, off
	v_add_co_u32_e32 v16, vcc, 0x1a147000, v14
	s_addc_u32 s11, s11, 0
	s_nop 0
	v_addc_co_u32_e32 v17, vcc, 0, v15, vcc
	v_add_co_u32_e32 v14, vcc, 0x1a148000, v14
	v_lshl_add_u64 v[8:9], v[8:9], 0, s[34:35]
	s_nop 0
	v_addc_co_u32_e32 v15, vcc, 0, v15, vcc
	v_cmp_lt_i32_e32 vcc, s31, v0
	s_or_b64 s[8:9], vcc, s[8:9]
	global_store_dword v[16:17], v21, off
	global_store_dword v[14:15], v18, off
	s_andn2_b64 exec, exec, s[8:9]
	s_cbranch_execnz .LBB0_595
	s_branch .LBB0_572
	s_nop 0
	s_nop 0
	s_nop 0
	s_nop 0
	s_nop 0
	s_nop 0
	s_nop 0
	s_nop 0
	s_nop 0
	s_nop 0
	s_nop 0
	s_nop 0
	s_nop 0
	s_nop 0
	s_nop 0
	s_nop 0
	s_nop 0
	s_nop 0
	s_nop 0
	s_nop 0
	s_nop 0
	s_nop 0
	s_nop 0
	s_nop 0
	s_nop 0
	s_nop 0
	s_nop 0
	s_nop 0
	s_nop 0
